# combo7 + mixer-A/B per-tile cross-half max exchange by v_permlane32_swap instead of a ds_bpermute round trip
# speedup vs baseline: 1.0044x; 1.0044x over previous
; #define LAS __attribute__((address_space(3)))
; template <int MODE> ...
;     ...
;             for (int ks = 0; ks < 4; ++ks) {
;                 const bf16x8 a0 = *(const LAS bf16x8*)(kb + 32 * ks);
;                 const bf16x8 a1 = *(const LAS bf16x8*)(kb + 32 * KP + 32 * ks);
;                 s0 = __builtin_amdgcn_mfma_f32_32x32x16_bf16(a0, qf[ks], s0, 0, 0, 0);
;                 s1 = __builtin_amdgcn_mfma_f32_32x32x16_bf16(a1, qf[ks], s1, 0, 0, 0);
;             }
;             if (MODE == 0) {
;                 const LAS float* bh = bias + (w >> 1) * 384 + (T * 64 - qpos + 192 + 8 * h);
; #pragma unroll
;                 for (int i = 0; i < 16; ++i) { const int o_ = 16 * (i >> 3) + (i & 7);
;                     s0[i] = s0[i] * C2 + bh[o_]; s1[i] = s1[i] * C2 + bh[o_ + 32]; }
;             } else if (MODE == 1) {
;                 const LAS float* bh = bias + (T - grow + 7) * 128 + (63 - (32 * (w & 1) + r) + 8 * h);
; #pragma unroll
;                 for (int i = 0; i < 16; ++i) { const int o_ = 16 * (i >> 3) + (i & 7);
;                     s0[i] = (s0[i] * C2 + bh[o_]) + pen0[i]; s1[i] = (s1[i] * C2 + bh[o_ + 32]) + pen1[i]; }
;             }
;             float mx = fmaxf(s0[0], s1[0]);
; #pragma unroll
;             for (int i = 1; i < 16; ++i) mx = fmaxf(mx, fmaxf(s0[i], s1[i]));
;             mx = fmaxf(mx, __shfl_xor(mx, 32));
;             const float mnew = fmaxf(m, mx);
;             const float alpha = __builtin_amdgcn_exp2f(m - mnew);
;             m = mnew;
;             float ps = 0.f;
; #pragma unroll
;             for (int i = 0; i < 16; ++i) { s0[i] = __builtin_amdgcn_exp2f(s0[i] - mnew); s1[i] = __builtin_amdgcn_exp2f(s1[i] - mnew); ps += s0[i] + s1[i]; }
;             l = l * alpha + ps;
; #pragma unroll
;             for (int i = 0; i < 16; ++i) { o0[i] *= alpha; o1[i] *= alpha; }
.LBB0_294:
	s_and_b32 s4, s11, 1
	s_mul_i32 s5, s4, 0x2400
	v_add_u32_e32 v189, s5, v128
	ds_read_b128 v[32:35], v189
	ds_read_b128 v[190:193], v189 offset:32
	ds_read_b128 v[48:51], v189 offset:4608
	ds_read_b128 v[194:197], v189 offset:4640
	s_andn2_b64 vcc, exec, s[20:21]
	s_waitcnt lgkmcnt(3)
	v_mfma_f32_32x32x16_bf16 v[32:47], v[32:35], v[64:67], 0
	s_waitcnt lgkmcnt(1)
	v_mfma_f32_32x32x16_bf16 v[48:63], v[48:51], v[64:67], 0
	v_mfma_f32_32x32x16_bf16 v[32:47], v[190:193], v[68:71], v[32:47]
	s_waitcnt lgkmcnt(0)
	v_mfma_f32_32x32x16_bf16 v[48:63], v[194:197], v[68:71], v[48:63]
	ds_read_b128 v[190:193], v189 offset:64
	ds_read_b128 v[194:197], v189 offset:96
	s_waitcnt lgkmcnt(1)
	v_mfma_f32_32x32x16_bf16 v[32:47], v[190:193], v[72:75], v[32:47]
	ds_read_b128 v[190:193], v189 offset:4672
	ds_read_b128 v[200:203], v189 offset:4704
	s_waitcnt lgkmcnt(1)
	v_mfma_f32_32x32x16_bf16 v[48:63], v[190:193], v[72:75], v[48:63]
	ds_read2_b32 v[190:191], v187 offset1:1
	v_mfma_f32_32x32x16_bf16 v[32:47], v[194:197], v[76:79], v[32:47]
	ds_read2_b32 v[192:193], v187 offset0:2 offset1:3
	ds_read2_b32 v[194:195], v187 offset0:4 offset1:5
	ds_read2_b32 v[196:197], v187 offset0:6 offset1:7
	ds_read2_b32 v[204:205], v187 offset0:32 offset1:33
	ds_read2_b32 v[206:207], v187 offset0:34 offset1:35
	ds_read2_b32 v[210:211], v187 offset0:36 offset1:37
	ds_read2_b32 v[212:213], v187 offset0:38 offset1:39
	s_waitcnt lgkmcnt(7)
	s_nop 3
	v_fmamk_f32 v189, v32, 0x3e38aa3b, v190
	v_mfma_f32_32x32x16_bf16 v[48:63], v[200:203], v[76:79], v[48:63]
	v_fmac_f32_e32 v191, 0x3e38aa3b, v33
	s_waitcnt lgkmcnt(6)
	v_fmac_f32_e32 v193, 0x3e38aa3b, v35
	s_waitcnt lgkmcnt(5)
	v_fmac_f32_e32 v195, 0x3e38aa3b, v37
	s_waitcnt lgkmcnt(4)
	v_fmac_f32_e32 v197, 0x3e38aa3b, v39
	s_waitcnt lgkmcnt(3)
	s_nop 3
	v_fmac_f32_e32 v205, 0x3e38aa3b, v49
	v_fmamk_f32 v49, v34, 0x3e38aa3b, v192
	s_waitcnt lgkmcnt(2)
	v_fmac_f32_e32 v207, 0x3e38aa3b, v51
	v_fmamk_f32 v51, v36, 0x3e38aa3b, v194
	s_waitcnt lgkmcnt(1)
	v_fmac_f32_e32 v211, 0x3e38aa3b, v53
	v_fmamk_f32 v53, v38, 0x3e38aa3b, v196
	s_waitcnt lgkmcnt(0)
	v_fmamk_f32 v190, v54, 0x3e38aa3b, v212
	v_fmac_f32_e32 v213, 0x3e38aa3b, v55
	ds_read2_b32 v[54:55], v187 offset0:16 offset1:17
	ds_read2_b32 v[36:37], v187 offset0:48 offset1:49
	ds_read2_b32 v[200:201], v187 offset0:18 offset1:19
	ds_read2_b32 v[202:203], v187 offset0:20 offset1:21
	ds_read2_b32 v[214:215], v187 offset0:22 offset1:23
	ds_read2_b32 v[38:39], v187 offset0:50 offset1:51
	ds_read2_b32 v[34:35], v187 offset0:52 offset1:53
	ds_read2_b32 v[32:33], v187 offset0:54 offset1:55
	v_fmamk_f32 v48, v48, 0x3e38aa3b, v204
	v_fmamk_f32 v50, v50, 0x3e38aa3b, v206
	v_fmamk_f32 v52, v52, 0x3e38aa3b, v210
	s_waitcnt lgkmcnt(6)
	v_fmamk_f32 v196, v56, 0x3e38aa3b, v36
	s_waitcnt lgkmcnt(0)
	v_fmamk_f32 v210, v62, 0x3e38aa3b, v32
	v_max_f32_e32 v32, v191, v205
	v_fmamk_f32 v208, v60, 0x3e38aa3b, v34
	v_max3_f32 v32, v189, v48, v32
	v_max_f32_e32 v34, v49, v50
	v_max_f32_e32 v36, v193, v207
	v_max3_f32 v32, v32, v34, v36
	v_max_f32_e32 v34, v51, v52
	v_max_f32_e32 v36, v195, v211
	v_fmamk_f32 v54, v40, 0x3e38aa3b, v54
	v_fmac_f32_e32 v55, 0x3e38aa3b, v41
	v_fmac_f32_e32 v37, 0x3e38aa3b, v57
	v_max3_f32 v32, v32, v34, v36
	v_max_f32_e32 v34, v53, v190
	v_max_f32_e32 v36, v197, v213
	v_fmamk_f32 v56, v42, 0x3e38aa3b, v200
	v_fmamk_f32 v198, v58, 0x3e38aa3b, v38
	v_fmac_f32_e32 v201, 0x3e38aa3b, v43
	v_fmac_f32_e32 v39, 0x3e38aa3b, v59
	v_max3_f32 v32, v32, v34, v36
	v_max_f32_e32 v34, v54, v196
	v_max_f32_e32 v36, v55, v37
	v_fmamk_f32 v58, v44, 0x3e38aa3b, v202
	v_fmac_f32_e32 v203, 0x3e38aa3b, v45
	v_fmac_f32_e32 v35, 0x3e38aa3b, v61
	v_max3_f32 v32, v32, v34, v36
	v_max_f32_e32 v34, v56, v198
	v_max_f32_e32 v36, v201, v39
	v_fmamk_f32 v60, v46, 0x3e38aa3b, v214
	v_fmac_f32_e32 v215, 0x3e38aa3b, v47
	v_fmac_f32_e32 v33, 0x3e38aa3b, v63
	v_max3_f32 v32, v32, v34, v36
	v_max_f32_e32 v34, v58, v208
	v_max_f32_e32 v36, v203, v35
	v_max3_f32 v32, v32, v34, v36
	v_max_f32_e32 v34, v60, v210
	v_max_f32_e32 v36, v215, v33
	v_max3_f32 v32, v32, v34, v36
	v_mov_b32_e32 v34, v32
	s_nop 1
	v_permlane32_swap_b32_e32 v34, v32
	s_waitcnt lgkmcnt(0)
	v_max3_f32 v34, v188, v32, v34
	v_sub_f32_e32 v42, v49, v34
	v_sub_f32_e32 v49, v211, v34
	v_add_u32_e32 v211, s5, v186
	v_sub_f32_e32 v32, v188, v34
	v_sub_f32_e32 v36, v189, v34
	v_sub_f32_e32 v40, v191, v34
	v_sub_f32_e32 v46, v51, v34
	v_sub_f32_e32 v51, v190, v34
	ds_read_b128 v[188:191], v211 offset:18432
	v_sub_f32_e32 v38, v48, v34
	v_sub_f32_e32 v43, v50, v34
	v_sub_f32_e32 v44, v193, v34
	v_sub_f32_e32 v47, v52, v34
	v_sub_f32_e32 v48, v195, v34
	v_sub_f32_e32 v50, v53, v34
	v_sub_f32_e32 v52, v197, v34
	v_exp_f32_e32 v32, v32
	v_exp_f32_e32 v36, v36
	v_exp_f32_e32 v40, v40
	v_exp_f32_e32 v42, v42
	v_exp_f32_e32 v44, v44
	v_exp_f32_e32 v46, v46
	v_exp_f32_e32 v48, v48
	v_exp_f32_e32 v50, v50
	v_exp_f32_e32 v52, v52
	v_sub_f32_e32 v57, v201, v34
	v_sub_f32_e32 v59, v203, v34
	ds_read_b128 v[192:195], v211 offset:23040
	ds_read_b128 v[200:203], v211 offset:18464
	v_sub_f32_e32 v197, v60, v34
	v_cvt_pk_bf16_f32 v60, v36, v40
	v_cvt_pk_bf16_f32 v61, v42, v44
	v_cvt_pk_bf16_f32 v62, v46, v48
	v_cvt_pk_bf16_f32 v63, v50, v52
	v_cmp_neq_f32_e64 s[100:101], 1.0, v32
	s_nop 1
	s_mov_b64 exec, s[100:101]
	s_cbranch_execz .Lal_a1
	v_pk_mul_f32 v[14:15], v[14:15], v[32:33] op_sel_hi:[1,0]
	v_pk_mul_f32 v[12:13], v[12:13], v[32:33] op_sel_hi:[1,0]
	v_pk_mul_f32 v[10:11], v[10:11], v[32:33] op_sel_hi:[1,0]
	v_pk_mul_f32 v[8:9], v[8:9], v[32:33] op_sel_hi:[1,0]
	v_pk_mul_f32 v[6:7], v[6:7], v[32:33] op_sel_hi:[1,0]
	v_pk_mul_f32 v[4:5], v[4:5], v[32:33] op_sel_hi:[1,0]
	v_pk_mul_f32 v[2:3], v[2:3], v[32:33] op_sel_hi:[1,0]
	v_pk_mul_f32 v[0:1], v[0:1], v[32:33] op_sel_hi:[1,0]
	v_pk_mul_f32 v[30:31], v[30:31], v[32:33] op_sel_hi:[1,0]
	v_pk_mul_f32 v[28:29], v[28:29], v[32:33] op_sel_hi:[1,0]

; #define LAS __attribute__((address_space(3)))
; __device__ __forceinline__ void attn_b_unit(LAS unsigned char* lds, const bf16_t* proj, const bf16_t* vt, bf16_t* obuf, int b, int hk, int blk, const float* btab, unsigned long long* sg, bool build_lut, CP WP, int wlayer, int wbase) {
;     ...
;         if (T >= wlo && T <= whi) {
;             const LAS unsigned char* kb = lds + ATT_K + buf * ATT_TILE + (kc0 + pr) * KP + 16 * h;
;             f32x16 s0;
; #pragma unroll
;             for (int i = 0; i < 16; ++i) s0[i] = 0.f;
; #pragma unroll
;             for (int ks = 0; ks < 4; ++ks) s0 = __builtin_amdgcn_mfma_f32_32x32x16_bf16(*(const LAS bf16x8*)(kb + 32 * ks), qf[ks], s0, 0, 0, 0);
;             const int dr = (T >= rsq && T < rsq + 8) ? T - rq + 7 : 15;
;             const LAS float* bh = bias + dr * 128 + (kc0 + 8 * h - c + 63);
; #pragma unroll
;             for (int i = 0; i < 16; ++i) s0[i] = (s0[i] * C2 + bh[16 * (i >> 3) + (i & 7)]) + pen[i];
;             float mx = s0[0];
; #pragma unroll
;             for (int i = 1; i < 16; ++i) mx = fmaxf(mx, s0[i]);
;             mx = fmaxf(mx, __shfl_xor(mx, 32));
;             const float mnew = fmaxf(mrun, mx);
;             const float alpha = __builtin_amdgcn_exp2f(mrun - mnew);
;             mrun = mnew;
;             float ps = 0.f;
; #pragma unroll
;             for (int i = 0; i < 16; ++i) { s0[i] = __builtin_amdgcn_exp2f(s0[i] - mnew); ps += s0[i]; }
;             l = l * alpha + ps;
; #pragma unroll
;             for (int i = 0; i < 16; ++i) { o0[i] *= alpha; o1[i] *= alpha; }
.LBB0_379:
	s_add_i32 s6, s51, s20
	s_and_b32 s10, s20, 1
	s_cmp_gt_u32 s4, s6
	s_cselect_b64 s[30:31], -1, 0
	s_and_b64 s[30:31], s[22:23], s[30:31]
	s_cmp_gt_u32 s6, s21
	s_cselect_b64 s[34:35], -1, 0
	s_or_b64 s[30:31], s[30:31], s[34:35]
	s_and_b64 vcc, exec, s[30:31]
	s_cbranch_vccnz .LBB0_381
	s_mul_i32 s11, s10, 0x2400
	v_add_u32_e32 v193, s11, v187
	ds_read_b128 v[32:35], v193
	ds_read_b128 v[194:197], v193 offset:32
	v_cmp_ge_u32_e32 vcc, s6, v186
	v_cmp_lt_u32_e64 s[6:7], s6, v188
	s_and_b64 vcc, vcc, s[6:7]
	s_waitcnt lgkmcnt(1)
	v_mfma_f32_32x32x16_bf16 v[32:47], v[32:35], v[48:51], 0
	s_waitcnt lgkmcnt(0)
	v_mfma_f32_32x32x16_bf16 v[32:47], v[194:197], v[52:55], v[32:47]
	ds_read_b128 v[194:197], v193 offset:64
	s_waitcnt lgkmcnt(0)
	v_mfma_f32_32x32x16_bf16 v[32:47], v[194:197], v[56:59], v[32:47]
	ds_read_b128 v[194:197], v193 offset:96
	v_cndmask_b32_e32 v193, v225, v191, vcc
	v_lshl_add_u32 v193, v193, 2, v189
	s_waitcnt lgkmcnt(0)
	v_mfma_f32_32x32x16_bf16 v[32:47], v[194:197], v[60:63], v[32:47]
	v_add_u32_e32 v194, 0x90fc, v193
	ds_read2_b32 v[194:195], v194 offset1:1
	s_waitcnt lgkmcnt(0)
	s_nop 8
	v_fmamk_f32 v32, v32, 0x3e38aa3b, v194
	v_add_f32_e32 v194, v157, v32
	v_add_u32_e32 v32, 0x9104, v193
	v_fmac_f32_e32 v195, 0x3e38aa3b, v33
	ds_read2_b32 v[32:33], v32 offset1:1
	v_add_f32_e32 v195, v159, v195
	s_waitcnt lgkmcnt(0)
	v_fmamk_f32 v32, v34, 0x3e38aa3b, v32
	v_add_f32_e32 v34, v160, v32
	v_fmac_f32_e32 v33, 0x3e38aa3b, v35
	v_add_u32_e32 v32, 0x910c, v193
	v_add_f32_e32 v35, v161, v33
	ds_read2_b32 v[32:33], v32 offset1:1
	s_waitcnt lgkmcnt(0)
	v_fmamk_f32 v32, v36, 0x3e38aa3b, v32
	v_add_f32_e32 v196, v162, v32
	v_fmac_f32_e32 v33, 0x3e38aa3b, v37
	v_add_u32_e32 v32, 0x9114, v193
	v_add_f32_e32 v37, v163, v33
	ds_read2_b32 v[32:33], v32 offset1:1
	v_max_f32_e32 v36, v194, v195
	v_max3_f32 v36, v36, v34, v35
	v_max3_f32 v36, v36, v196, v37
	s_waitcnt lgkmcnt(0)
	v_fmamk_f32 v32, v38, 0x3e38aa3b, v32
	v_add_f32_e32 v38, v164, v32
	v_fmac_f32_e32 v33, 0x3e38aa3b, v39
	v_add_u32_e32 v32, 0x913c, v193
	v_add_f32_e32 v39, v165, v33
	ds_read2_b32 v[32:33], v32 offset1:1
	v_max3_f32 v36, v36, v38, v39
	s_waitcnt lgkmcnt(0)
	v_fmamk_f32 v32, v40, 0x3e38aa3b, v32
	v_add_f32_e32 v40, v166, v32
	v_fmac_f32_e32 v33, 0x3e38aa3b, v41
	v_add_u32_e32 v32, 0x9144, v193
	v_add_f32_e32 v41, v167, v33
	ds_read2_b32 v[32:33], v32 offset1:1
	v_max3_f32 v36, v36, v40, v41
	s_waitcnt lgkmcnt(0)
	v_fmamk_f32 v32, v42, 0x3e38aa3b, v32
	v_add_f32_e32 v42, v168, v32
	v_fmac_f32_e32 v33, 0x3e38aa3b, v43
	v_add_u32_e32 v32, 0x914c, v193
	v_add_f32_e32 v43, v169, v33
	ds_read2_b32 v[32:33], v32 offset1:1
	v_max3_f32 v36, v36, v42, v43
	s_waitcnt lgkmcnt(0)
	v_fmamk_f32 v32, v44, 0x3e38aa3b, v32
	v_add_f32_e32 v44, v182, v32
	v_fmac_f32_e32 v33, 0x3e38aa3b, v45
	v_add_u32_e32 v32, 0x9154, v193
	v_add_f32_e32 v45, v183, v33
	ds_read2_b32 v[32:33], v32 offset1:1
	v_max3_f32 v36, v36, v44, v45
	s_waitcnt lgkmcnt(0)
	v_fmamk_f32 v32, v46, 0x3e38aa3b, v32
	v_fmac_f32_e32 v33, 0x3e38aa3b, v47
	v_add_f32_e32 v32, v184, v32
	v_add_f32_e32 v33, v185, v33
	v_max3_f32 v36, v36, v32, v33
	v_mov_b32_e32 v46, v36
	s_nop 1
	v_permlane32_swap_b32_e32 v46, v36
	s_waitcnt lgkmcnt(0)
	v_max3_f32 v46, v192, v36, v46
	v_sub_f32_e32 v38, v38, v46
	v_sub_f32_e32 v47, v194, v46
	v_exp_f32_e32 v194, v38
	v_sub_f32_e32 v38, v39, v46
	v_sub_f32_e32 v36, v192, v46
	v_sub_f32_e32 v192, v195, v46
	v_exp_f32_e32 v195, v38
	v_sub_f32_e32 v38, v40, v46
	v_exp_f32_e32 v39, v38
	v_sub_f32_e32 v38, v41, v46
	v_exp_f32_e32 v47, v47
	v_exp_f32_e32 v40, v38
	v_sub_f32_e32 v38, v42, v46
	v_exp_f32_e32 v192, v192
	v_sub_f32_e32 v34, v34, v46
	v_exp_f32_e32 v41, v38
	v_sub_f32_e32 v38, v43, v46
	v_exp_f32_e32 v34, v34
	v_sub_f32_e32 v35, v35, v46
	v_exp_f32_e32 v42, v38
	v_sub_f32_e32 v38, v44, v46
	v_sub_f32_e32 v32, v32, v46
	v_exp_f32_e32 v35, v35
	v_sub_f32_e32 v193, v196, v46
	v_exp_f32_e32 v43, v38
	v_sub_f32_e32 v38, v45, v46
	v_exp_f32_e32 v45, v32
	v_sub_f32_e32 v32, v33, v46
	v_exp_f32_e32 v193, v193
	v_sub_f32_e32 v37, v37, v46
	v_exp_f32_e32 v196, v32
	v_add_f32_e32 v32, 0, v47
	v_exp_f32_e32 v37, v37
	v_add_f32_e32 v32, v192, v32
	v_add_f32_e32 v32, v34, v32
	v_add_f32_e32 v32, v35, v32
	v_add_f32_e32 v32, v193, v32
	v_add_f32_e32 v32, v37, v32
	v_add_f32_e32 v32, v194, v32
	v_add_f32_e32 v32, v195, v32
	v_add_f32_e32 v32, v39, v32
	v_exp_f32_e32 v44, v38
	v_add_f32_e32 v32, v40, v32
	v_add_f32_e32 v32, v41, v32
	v_exp_f32_e32 v36, v36
	v_add_f32_e32 v32, v42, v32
	v_add_f32_e32 v32, v43, v32
	v_add_f32_e32 v32, v44, v32
	v_add_f32_e32 v32, v45, v32
	v_add_f32_e32 v197, v196, v32
	v_cvt_pk_bf16_f32 v32, v39, v40
	v_cvt_pk_bf16_f32 v40, v193, v37
	v_cmp_neq_f32_e64 s[100:101], 1.0, v36
	s_nop 1
	s_mov_b64 exec, s[100:101]
	s_cbranch_execz .Lal_b1
	v_pk_mul_f32 v[14:15], v[14:15], v[36:37] op_sel_hi:[1,0]
	v_pk_mul_f32 v[12:13], v[12:13], v[36:37] op_sel_hi:[1,0]
	v_pk_mul_f32 v[10:11], v[10:11], v[36:37] op_sel_hi:[1,0]
	v_pk_mul_f32 v[8:9], v[8:9], v[36:37] op_sel_hi:[1,0]
	v_pk_mul_f32 v[6:7], v[6:7], v[36:37] op_sel_hi:[1,0]
	v_pk_mul_f32 v[4:5], v[4:5], v[36:37] op_sel_hi:[1,0]
	v_pk_mul_f32 v[2:3], v[2:3], v[36:37] op_sel_hi:[1,0]
	v_pk_mul_f32 v[0:1], v[0:1], v[36:37] op_sel_hi:[1,0]
	v_pk_mul_f32 v[30:31], v[30:31], v[36:37] op_sel_hi:[1,0]
	v_pk_mul_f32 v[28:29], v[28:29], v[36:37] op_sel_hi:[1,0]
	v_pk_mul_f32 v[26:27], v[26:27], v[36:37] op_sel_hi:[1,0]
	v_pk_mul_f32 v[24:25], v[24:25], v[36:37] op_sel_hi:[1,0]
	v_pk_mul_f32 v[22:23], v[22:23], v[36:37] op_sel_hi:[1,0]
	v_pk_mul_f32 v[20:21], v[20:21], v[36:37] op_sel_hi:[1,0]
	v_pk_mul_f32 v[18:19], v[18:19], v[36:37] op_sel_hi:[1,0]
	v_pk_mul_f32 v[16:17], v[16:17], v[36:37] op_sel_hi:[1,0]
